# m2 phase: half of the workgroups run the RG-LRU item first (VALU-bound) while the other half stream retention/SSD operands
# baseline (speedup 1.0000x reference)
; #define LAS __attribute__((address_space(3)))
;     __device__ bool next(int i, Unit& u) const {
;         const long L = (long)i * G + c; if (L >= nwg) return false;
;         int wgid = (int)L; { const int q = nwg / NXCD, r = nwg % NXCD, xcd = wgid % NXCD, off = wgid / NXCD; wgid = (xcd < r ? xcd * (q + 1) : r * (q + 1) + (xcd - r) * q) + off; }
;         const int nig = WGM * nN, gid = wgid / nig, fm = gid * WGM, gsz = (nM - fm) < WGM ? (nM - fm) : WGM;
;         u.pm = fm + ((wgid % nig) % gsz); u.pn = (wgid % nig) / gsz; return true;
; __global__ void __launch_bounds__(512, 2) mega(Params p, int ph0, int ph1, int coop) {
;     extern __shared__ __attribute__((aligned(16))) unsigned char shm[];
;     LAS unsigned char* lds = (LAS unsigned char*)shm;
;     cg::grid_group grid = cg::this_grid();
;     volatile LAS unsigned* st = (volatile LAS unsigned*)(lds + LDS_BYTES);
;     if (threadIdx.x < 4) st[threadIdx.x] = 0u;
;     __syncthreads();
;     XcdBarrier xb = xcd_barrier_post((unsigned*)(p.ws + W_BAR), st);
.LBB0_6:
	s_lshl_b32 s33, s94, 3
	s_mov_b32 s14, s2
	s_lshl_b32 s2, s2, 3
	s_add_u32 s26, s88, 0xa2a5600
	v_writelane_b32 v250, s12, 2
	s_addc_u32 s27, s89, 0
	s_cmpk_lt_i32 s14, 0xdc0
	v_writelane_b32 v250, s13, 3
	v_writelane_b32 v250, s2, 4
	s_cselect_b64 s[2:3], -1, 0
	v_writelane_b32 v250, s2, 5
	s_load_dwordx16 s[36:51], s[0:1], 0xc0
	v_mov_b32_e32 v162, 0x358637bd
	v_writelane_b32 v250, s3, 6
	s_add_u32 s2, s88, 0x5800000
	v_writelane_b32 v250, s2, 7
	s_addc_u32 s2, s89, 0
	v_writelane_b32 v250, s2, 8
	s_add_u32 s2, s88, 0x2c00000
	v_writelane_b32 v250, s2, 9
	s_addc_u32 s2, s89, 0
	v_writelane_b32 v250, s2, 10
	s_add_u32 s2, s88, 0x2000000
	v_writelane_b32 v250, s2, 11
	s_addc_u32 s2, s89, 0
	v_writelane_b32 v250, s2, 12
	s_lshl_b32 s2, s14, 9
	s_lshl_b32 s28, s94, 9
	v_writelane_b32 v250, s2, 13
	s_add_u32 s2, s88, 0x6e00000
	s_addc_u32 s3, s89, 0
	s_add_u32 s54, s88, 0x6e80000
	s_addc_u32 s55, s89, 0
	s_add_u32 s52, s88, 0x6ec0080
	s_addc_u32 s53, s89, 0
	s_add_u32 s60, s88, 0x7103200
	s_addc_u32 s61, s89, 0
	s_add_u32 s18, s88, 0x17445600
	v_writelane_b32 v250, s2, 14
	s_addc_u32 s19, s89, 0
	s_ashr_i32 s13, s94, 31
	s_ashr_i32 s15, s14, 31
	v_writelane_b32 v250, s3, 15
	s_add_u32 s2, s88, 0x1d449600
	s_addc_u32 s3, s89, 0
	v_writelane_b32 v250, s2, 16
	v_mov_b32_e32 v224, 0x40135761
	v_mov_b32_e32 v225, 0x3ecc95a3
	v_writelane_b32 v250, s3, 17
	s_add_u32 s2, s88, 0x1d709600
	s_addc_u32 s3, s89, 0
	v_writelane_b32 v250, s2, 18
	v_mov_b32_e32 v226, 0x3c0881c4
	v_mov_b32_e32 v227, 0xbab64f3b
	v_writelane_b32 v250, s3, 19
	s_add_u32 s2, s88, 0x1d9c9600
	s_addc_u32 s3, s89, 0
	v_writelane_b32 v250, s2, 20
	s_cmpk_lt_i32 s14, 0x100
	v_mov_b32_e32 v228, 1
	v_writelane_b32 v250, s3, 21
	s_cselect_b64 s[2:3], -1, 0
	s_lshr_b32 s4, s15, 29
	s_add_i32 s4, s14, s4
	s_ashr_i32 s10, s4, 3
	s_and_b32 s4, s4, -8
	s_sub_i32 s5, s14, s4
	v_writelane_b32 v250, s2, 22
	s_lshl_b32 s6, s5, 5
	s_mul_i32 s9, s5, 33
	v_writelane_b32 v250, s3, 23
	s_add_u32 s2, s88, 0xc2a5600
	s_addc_u32 s3, s89, 0
	v_writelane_b32 v250, s2, 24
	s_add_i32 s4, s94, 0x1ff
	v_bfrev_b32_e32 v229, 0.5
	v_writelane_b32 v250, s3, 25
	s_add_u32 s2, s88, 0x1cc45600
	s_addc_u32 s3, s89, 0
	v_writelane_b32 v250, s2, 26
	v_mov_b64_e32 v[164:165], 0xff
	v_mov_b64_e32 v[166:167], 0x100
	v_writelane_b32 v250, s3, 27
	s_waitcnt lgkmcnt(0)
	s_add_u32 s2, s50, 0x11720000
	v_writelane_b32 v250, s2, 28
	s_addc_u32 s2, s51, 0
	s_cmpk_lt_i32 s14, 0x580
	v_writelane_b32 v250, s2, 29
	s_cselect_b64 s[2:3], -1, 0
	v_writelane_b32 v250, s2, 30
	s_lshl_b32 s7, s5, 7
	s_cmp_lt_i32 s5, 0
	v_writelane_b32 v250, s3, 31
	s_movk_i32 s2, 0xb1
	s_cselect_b32 s12, s9, s6
	s_cselect_b32 s6, s2, 0xb0
	s_mul_i32 s6, s6, s5
	s_mulk_i32 s5, 0x81
	s_cselect_b32 s11, s5, s7
	s_add_i32 s6, s6, s10
	s_mul_hi_i32 s5, s6, 0x2e8ba2e9
	s_lshr_b32 s7, s5, 31
	s_ashr_i32 s5, s5, 5
	s_add_i32 s5, s5, s7
	s_mul_i32 s7, s5, 0xb0
	s_sub_i32 s6, s6, s7
	s_bfe_u32 s7, s6, 0x3001c
	s_add_i32 s7, s6, s7
	s_and_b32 s9, s7, 0xfff8
	s_sub_i32 s6, s6, s9
	s_lshl_b32 s5, s5, 3
	s_sext_i32_i16 s7, s7
	s_sext_i32_i16 s6, s6
	s_add_i32 s24, s5, s6
	s_lshr_b32 s6, s7, 3
	s_ashr_i32 s2, s7, 3
	s_bfe_i64 s[6:7], s[6:7], 0x100000
	v_writelane_b32 v250, s2, 32
	s_lshl_b64 s[2:3], s[6:7], 19
	v_writelane_b32 v250, s2, 33
	s_ashr_i32 s25, s24, 31
	s_lshl_b64 s[6:7], s[24:25], 19
	v_writelane_b32 v250, s3, 34
	s_mov_b32 s2, s24
	v_writelane_b32 v250, s2, 35
	v_mov_b32_e32 v169, 0x3e000000
	v_mov_b32_e32 v230, 0x42800000
	v_writelane_b32 v250, s3, 36
	s_add_u32 s2, s26, s6
	s_addc_u32 s3, s27, s7
	s_add_u32 s6, s2, 0x40000
	v_writelane_b32 v250, s2, 37
	s_addc_u32 s7, s3, 0
	v_not_b32_e32 v231, 63
	v_writelane_b32 v250, s3, 38
	v_writelane_b32 v250, s6, 39
	s_add_u32 s2, s50, 0x117d0000
	v_mov_b32_e32 v170, 0x3f317218
	v_writelane_b32 v250, s7, 40
	v_writelane_b32 v250, s2, 41
	s_addc_u32 s2, s51, 0
	s_cmpk_eq_i32 s94, 0x100
	s_cselect_b32 s5, 0x80, 0
	s_cselect_b32 s6, 0x80, s94
	s_cmp_ge_i32 s14, s5
	v_writelane_b32 v250, s2, 42
	s_cselect_b64 s[2:3], -1, 0
	s_sub_i32 s5, s14, s5
	s_add_i32 s7, s6, 0x57f
	s_add_u32 s24, s88, 0x7245600
	v_writelane_b32 v250, s2, 43
	s_addc_u32 s25, s89, 0
	v_mov_b32_e32 v232, 0x7fc00000
	v_writelane_b32 v250, s3, 44
	s_add_u32 s2, s88, 0xa245600
	s_addc_u32 s3, s89, 0
	v_writelane_b32 v250, s2, 45
	s_cmpk_lt_i32 s14, 0x200
	v_mov_b32_e32 v233, 0xff800000
	v_writelane_b32 v250, s3, 46
	s_cselect_b64 s[2:3], -1, 0
	s_add_u32 s34, s88, 0xc2e5600
	s_addc_u32 s35, s89, 0
	s_add_u32 s58, s88, 0x143e5600
	s_addc_u32 s59, s89, 0
	s_add_u32 s84, s88, 0x153e5600
	v_writelane_b32 v250, s2, 47
	s_addc_u32 s85, s89, 0
	v_mov_b32_e32 v234, 0x7f800000
	v_writelane_b32 v250, s3, 48
	s_add_u32 s2, s88, 0x6f00200
	s_addc_u32 s3, s89, 0
	v_writelane_b32 v250, s2, 49
	v_mov_b32_e32 v235, 0x400
	v_mov_b32_e32 v238, 0x7f000000
	v_writelane_b32 v250, s3, 50
	s_add_u32 s2, s88, 0x7081200
	s_addc_u32 s3, s89, 0
	v_writelane_b32 v250, s2, 51
	v_mov_b32_e32 v241, 0x461c4000
	v_mov_b32_e32 v239, 0x4000
	v_writelane_b32 v250, s3, 52
	s_add_u32 s2, s88, 0x19445600
	s_addc_u32 s3, s89, 0
	v_writelane_b32 v250, s2, 53
	v_not_b32_e32 v240, 31
	s_movk_i32 s93, 0x1000
	v_writelane_b32 v250, s3, 54
	s_add_u32 s2, s88, 0x7101200
	s_addc_u32 s3, s89, 0
	v_writelane_b32 v250, s2, 55
	s_movk_i32 s87, 0x2000
	s_movk_i32 s97, 0x6000
	v_writelane_b32 v250, s3, 56
	s_add_u32 s2, s50, 0x8f20000
	s_addc_u32 s3, s51, 0
	v_writelane_b32 v250, s2, 57
	s_mov_b32 s96, 0xa000
	s_mov_b32 s31, 0xc000
	v_writelane_b32 v250, s3, 58
	s_add_u32 s2, s50, 0x44c0000
	s_addc_u32 s3, s51, 0
	v_writelane_b32 v250, s2, 59
	s_movk_i32 s92, 0x680
	s_mov_b64 s[90:91], 0x1000
; #define LAS __attribute__((address_space(3)))
; __global__ void __launch_bounds__(512, 2) mega(Params p, int ph0, int ph1, int coop) {
;     extern __shared__ __attribute__((aligned(16))) unsigned char shm[];
;     LAS unsigned char* lds = (LAS unsigned char*)shm;
;     cg::grid_group grid = cg::this_grid();
;     volatile LAS unsigned* st = (volatile LAS unsigned*)(lds + LDS_BYTES);
;     if (threadIdx.x < 4) st[threadIdx.x] = 0u;
;     __syncthreads();
;     XcdBarrier xb = xcd_barrier_post((unsigned*)(p.ws + W_BAR), st);
;     for (int ph = ph0; ph < ph1; ++ph) {
	v_writelane_b32 v250, s3, 60
	s_add_u32 s2, s88, 0x6f81200
	s_addc_u32 s3, s89, 0
	v_writelane_b32 v250, s2, 61
	s_mov_b32 s86, 0xbfb8aa3b
	s_nop 0
	v_writelane_b32 v250, s3, 62
	s_add_u32 s2, s50, 0x8920000
	v_writelane_b32 v250, s2, 63
	s_addc_u32 s2, s51, 0
	v_writelane_b32 v251, s2, 0
	s_add_u32 s2, s50, 0x9720000
	v_writelane_b32 v251, s2, 1
	s_addc_u32 s2, s51, 0
	v_writelane_b32 v251, s2, 2
	s_add_u32 s2, s50, 0x48c0000
	v_writelane_b32 v251, s2, 3
	s_addc_u32 s2, s51, 0
	v_writelane_b32 v251, s2, 4
	s_add_u32 s2, s50, 0x40b0000
	v_writelane_b32 v251, s2, 5
	v_writelane_b32 v251, s36, 6
	s_addc_u32 s2, s51, 0
	s_cmpk_lt_i32 s14, 0x400
	v_writelane_b32 v251, s37, 7
	v_writelane_b32 v251, s38, 8
	v_writelane_b32 v251, s39, 9
	v_writelane_b32 v251, s40, 10
	v_writelane_b32 v251, s41, 11
	v_writelane_b32 v251, s42, 12
	v_writelane_b32 v251, s43, 13
	v_writelane_b32 v251, s44, 14
	v_writelane_b32 v251, s45, 15
	v_writelane_b32 v251, s46, 16
	v_writelane_b32 v251, s47, 17
	v_writelane_b32 v251, s48, 18
	v_writelane_b32 v251, s49, 19
	v_writelane_b32 v251, s50, 20
	v_writelane_b32 v251, s51, 21
	v_writelane_b32 v251, s2, 22
	s_cselect_b64 s[2:3], -1, 0
	v_writelane_b32 v251, s2, 23
	s_nop 1
	v_writelane_b32 v251, s3, 24
	s_add_u32 s2, s88, 0x142e5600
	s_addc_u32 s3, s89, 0
	s_add_i32 s9, s94, 0x7ff
	v_writelane_b32 v251, s2, 25
	s_cmp_lg_u32 s22, 0
	s_nop 0
	v_writelane_b32 v251, s3, 26
	s_cselect_b64 s[2:3], -1, 0
	v_writelane_b32 v251, s2, 27
	s_nop 1
	v_writelane_b32 v251, s3, 28
	v_writelane_b32 v251, s20, 29
	s_cmp_eq_u32 s22, 2
	s_cselect_b64 s[2:3], -1, 0
	v_writelane_b32 v251, s21, 30
	v_writelane_b32 v251, s22, 31
	s_mov_b32 s23, 0
	v_writelane_b32 v251, s23, 32
	v_writelane_b32 v251, s2, 33
	s_mov_b32 s20, s28
	s_nop 0
	v_writelane_b32 v251, s3, 34
	s_add_u32 s2, s88, 0x1d445800
	s_addc_u32 s3, s89, 0
	v_writelane_b32 v251, s2, 35
	s_nop 1
	v_writelane_b32 v251, s3, 36
	s_add_u32 s2, s88, 0x1d445a00
	s_addc_u32 s3, s89, 0
	v_writelane_b32 v251, s2, 37
	s_nop 1
	v_writelane_b32 v251, s3, 38
	s_add_u32 s2, s88, 0x1d445b00
	s_addc_u32 s3, s89, 0
	v_writelane_b32 v251, s2, 39
	s_nop 1
	v_writelane_b32 v251, s3, 40
	s_add_u32 s2, s88, 0x1d445c00
	s_addc_u32 s3, s89, 0
	v_writelane_b32 v251, s2, 41
	s_nop 1
	v_writelane_b32 v251, s3, 42
	s_add_u32 s2, s88, 0x1d445d00
	s_addc_u32 s3, s89, 0
	v_writelane_b32 v251, s2, 43
	s_nop 1
	v_writelane_b32 v251, s3, 44
	s_add_u32 s2, s88, 0x1d445e00
	s_addc_u32 s3, s89, 0
	v_writelane_b32 v251, s2, 45
	s_nop 1
	v_writelane_b32 v251, s3, 46
	s_add_u32 s2, s88, 0x1d445f00
	s_addc_u32 s3, s89, 0
	v_writelane_b32 v251, s2, 47
	s_nop 1
	v_writelane_b32 v251, s3, 48
	s_add_u32 s2, s88, 0x1d446000
	s_addc_u32 s3, s89, 0
	v_writelane_b32 v251, s2, 49
	s_nop 1
	v_writelane_b32 v251, s3, 50
	s_add_u32 s2, s88, 0x1d446100
	s_addc_u32 s3, s89, 0
	v_writelane_b32 v251, s2, 51
	s_nop 1
	v_writelane_b32 v251, s3, 52
	s_add_u32 s2, s88, 0x1d446200
	s_addc_u32 s3, s89, 0
	v_writelane_b32 v251, s2, 53
	s_nop 1
	v_writelane_b32 v251, s3, 54
	s_add_u32 s2, s88, 0x1d446300
	s_addc_u32 s3, s89, 0
	v_writelane_b32 v251, s2, 55
	s_nop 1
	v_writelane_b32 v251, s3, 56
	s_add_u32 s2, s88, 0x1d446400
	s_addc_u32 s3, s89, 0
	v_writelane_b32 v251, s2, 57
	s_nop 1
	v_writelane_b32 v251, s3, 58
	s_add_u32 s2, s88, 0x1d446500
	s_addc_u32 s3, s89, 0
	v_writelane_b32 v251, s2, 59
	s_nop 1
	v_writelane_b32 v251, s3, 60
	s_add_u32 s2, s88, 0x1d446600
	s_addc_u32 s3, s89, 0
	v_writelane_b32 v251, s2, 61
	s_nop 1
	v_writelane_b32 v251, s3, 62
	s_add_u32 s2, s88, 0x1d446700
	s_addc_u32 s3, s89, 0
	v_writelane_b32 v251, s2, 63
	s_nop 1
	v_writelane_b32 v252, s3, 0
	s_add_u32 s2, s88, 0x1d446800
	s_addc_u32 s3, s89, 0
	v_writelane_b32 v252, s2, 1
	s_nop 1
	v_writelane_b32 v252, s3, 2
	s_add_u32 s2, s88, 0x1d446900
	s_addc_u32 s3, s89, 0
	v_writelane_b32 v252, s2, 3
	s_cmp_eq_u32 s8, 15
	s_nop 0
	v_writelane_b32 v252, s3, 4
	s_cselect_b64 s[2:3], -1, 0
	v_writelane_b32 v252, s2, 5
	s_cmp_eq_u32 s8, 14
	s_nop 0
	v_writelane_b32 v252, s3, 6
	s_cselect_b64 s[2:3], -1, 0
	v_writelane_b32 v252, s2, 7
	s_cmp_eq_u32 s8, 13
	s_nop 0
	v_writelane_b32 v252, s3, 8
	s_cselect_b64 s[2:3], -1, 0
	v_writelane_b32 v252, s2, 9
	s_cmp_eq_u32 s8, 12
	s_nop 0
	v_writelane_b32 v252, s3, 10
	s_cselect_b64 s[2:3], -1, 0
	v_writelane_b32 v252, s2, 11
	s_cmp_eq_u32 s8, 11
	s_nop 0
	v_writelane_b32 v252, s3, 12
	s_cselect_b64 s[2:3], -1, 0
	v_writelane_b32 v252, s2, 13
	s_cmp_eq_u32 s8, 10
	s_nop 0
	v_writelane_b32 v252, s3, 14
	s_cselect_b64 s[2:3], -1, 0
	v_writelane_b32 v252, s2, 15
	s_cmp_eq_u32 s8, 9
	s_nop 0
	v_writelane_b32 v252, s3, 16
	s_cselect_b64 s[2:3], -1, 0
	v_writelane_b32 v252, s2, 17
	s_cmp_eq_u32 s8, 8
	s_nop 0
	v_writelane_b32 v252, s3, 18
	s_cselect_b64 s[2:3], -1, 0
	v_writelane_b32 v252, s2, 19
	s_cmp_eq_u32 s8, 7
	s_nop 0
	v_writelane_b32 v252, s3, 20
	s_cselect_b64 s[2:3], -1, 0
	v_writelane_b32 v252, s2, 21
	s_cmp_eq_u32 s8, 6
	s_nop 0
	v_writelane_b32 v252, s3, 22
	s_cselect_b64 s[2:3], -1, 0
	v_writelane_b32 v252, s2, 23
	s_cmp_eq_u32 s8, 5
	s_nop 0
	v_writelane_b32 v252, s3, 24
	s_cselect_b64 s[2:3], -1, 0
	v_writelane_b32 v252, s2, 25
	s_cmp_eq_u32 s8, 4
	s_nop 0
	v_writelane_b32 v252, s3, 26
	s_cselect_b64 s[2:3], -1, 0
	v_writelane_b32 v252, s2, 27
	s_cmp_eq_u32 s8, 3
	s_nop 0
	v_writelane_b32 v252, s3, 28
	s_cselect_b64 s[2:3], -1, 0
	v_writelane_b32 v252, s2, 29
	s_cmp_eq_u32 s8, 2
	s_nop 0
	v_writelane_b32 v252, s3, 30
	s_cselect_b64 s[2:3], -1, 0
	v_writelane_b32 v252, s2, 31
	s_cmp_eq_u32 s8, 1
	s_nop 0
	v_writelane_b32 v252, s3, 32
	s_cselect_b64 s[2:3], -1, 0
	v_writelane_b32 v252, s2, 33
	s_cmp_eq_u32 s8, 0
	s_nop 0
; template <int K, int MODE  >
; __device__ __forceinline__ void thin_gemm(LAS unsigned char* lds, const bf16_t* A, const bf16_t* Bt, int N, void* out, int ldc, bf16_t* xb, u64* rss) {
;     ...
;     const int per = (ntask + (int)gridDim.x - 1) / (int)gridDim.x, t0 = blockIdx.x * per, t1 = min(ntask, t0 + per);
;     for (int base = t0; base < t1; base += 8) {
; __device__ __forceinline__ void thin_gemm_act(LAS unsigned char* lds, const bf16_t* A, const bf16_t* Bt, const u64* rss, const float* cw, const float* cb, const float* st, float* fo, bf16_t* act, int c0, int cnt) {
;     ...
;     const int per = (ntask + cnt - 1) / cnt, t0 = ((int)blockIdx.x - c0) * per, t1 = min(ntask, t0 + per);
;     for (int base = t0; base < t1; base += 8) {
	v_writelane_b32 v252, s3, 34
	s_cselect_b64 s[2:3], -1, 0
	v_writelane_b32 v252, s2, 35
	s_lshl_b32 s8, s8, 8
	s_nop 0
	v_writelane_b32 v252, s3, 36
	s_add_u32 s2, s16, s8
	s_addc_u32 s3, s17, 0
	s_add_u32 s16, s2, 0x1400
	s_addc_u32 s17, s3, 0
	v_writelane_b32 v252, s16, 37
	s_add_u32 s2, s2, 0x2400
	s_addc_u32 s3, s3, 0
	v_writelane_b32 v252, s17, 38
	v_writelane_b32 v252, s2, 39
	s_nop 1
	v_writelane_b32 v252, s3, 40
	s_add_u32 s2, s88, 0x1d448a00
	s_addc_u32 s3, s89, 0
	v_writelane_b32 v252, s2, 41
	s_nop 1
	v_writelane_b32 v252, s3, 42
	s_add_u32 s2, s88, 0x1d448b00
	s_addc_u32 s3, s89, 0
	v_writelane_b32 v252, s2, 43
	s_nop 1
	v_writelane_b32 v252, s3, 44
	s_add_i32 s2, s12, s10
	s_ashr_i32 s3, s2, 31
	s_lshr_b32 s3, s3, 27
	s_add_i32 s3, s2, s3
	s_and_b32 s8, s3, 0xffe0
	s_sub_i32 s2, s2, s8
	s_bfe_i32 s8, s2, 0x80000
	s_bfe_u32 s8, s8, 0x3000c
	s_add_i32 s8, s2, s8
	s_and_b32 s12, s8, 0xf8
	s_sub_i32 s2, s2, s12
	s_ashr_i32 s3, s3, 5
	s_lshl_b32 s3, s3, 3
	s_sext_i32_i8 s2, s2
	s_add_i32 s12, s3, s2
	s_add_i32 s2, s11, s10
	s_ashr_i32 s3, s2, 31
	s_lshr_b32 s3, s3, 25
	s_add_i32 s3, s2, s3
	s_and_b32 s10, s3, 0xff80
	s_sub_i32 s2, s2, s10
	s_bfe_i32 s10, s2, 0x80000
	s_bfe_u32 s10, s10, 0x3000c
	s_bfe_i32 s8, s8, 0x80000
	s_add_i32 s10, s2, s10
	s_sext_i32_i16 s8, s8
	s_and_b32 s11, s10, 0xf8
	s_ashr_i32 s8, s8, 3
	s_sub_i32 s2, s2, s11
	v_writelane_b32 v252, s8, 45
	s_ashr_i32 s3, s3, 7
	s_bfe_i32 s8, s10, 0x80000
	s_lshl_b32 s3, s3, 3
	s_sext_i32_i16 s8, s8
	s_sext_i32_i8 s2, s2
	s_add_i32 s10, s3, s2
	s_ashr_i32 s2, s8, 3
	v_writelane_b32 v252, s2, 46
	s_lshr_b32 s2, s8, 3
	s_bfe_i64 s[2:3], s[2:3], 0x100000
	s_lshl_b64 s[2:3], s[2:3], 19
	v_writelane_b32 v252, s2, 47
	s_ashr_i32 s11, s10, 31
	s_nop 0
	v_writelane_b32 v252, s3, 48
	s_mov_b32 s2, s10
	v_writelane_b32 v252, s2, 49
	s_nop 1
	v_writelane_b32 v252, s3, 50
	s_lshl_b64 s[2:3], s[10:11], 19
	s_add_u32 s2, s26, s2
	v_writelane_b32 v252, s26, 51
	s_addc_u32 s3, s27, s3
	s_add_u32 s10, s2, 0x40000
	v_writelane_b32 v252, s27, 52
	v_writelane_b32 v252, s2, 53
	s_addc_u32 s11, s3, 0
	s_movk_i32 s27, 0x4000
	v_writelane_b32 v252, s3, 54
	v_writelane_b32 v252, s10, 55
	s_mul_i32 s3, s12, 0x160000
	s_mul_hi_i32 s2, s12, 0x160000
	v_writelane_b32 v252, s11, 56
	s_add_u32 s10, s18, s3
	v_writelane_b32 v252, s18, 57
	s_addc_u32 s11, s19, s2
	s_add_u32 s2, s10, 0xb0000
	v_writelane_b32 v252, s19, 58
	v_writelane_b32 v252, s10, 59
	s_addc_u32 s3, s11, 0
	s_nop 0
	v_writelane_b32 v252, s11, 60
	v_writelane_b32 v252, s2, 61
	s_nop 1
	v_writelane_b32 v252, s3, 62
	s_mul_i32 s3, s12, 0xc0000
	s_mul_hi_i32 s2, s12, 0xc0000
	s_add_u32 s10, s24, s3
	v_writelane_b32 v253, s24, 0
	s_addc_u32 s11, s25, s2
	s_add_u32 s2, s10, 0x60000
	v_writelane_b32 v253, s25, 1
	v_writelane_b32 v253, s10, 2
	s_addc_u32 s3, s11, 0
	v_writelane_b32 v252, s12, 63
	v_writelane_b32 v253, s11, 3
	v_writelane_b32 v253, s2, 4
	s_mov_b32 s25, 0x8000
	s_nop 0
	v_writelane_b32 v253, s3, 5
	s_abs_i32 s2, s94
	v_cvt_f32_u32_e32 v1, s2
	s_sub_i32 s3, 0, s2
	v_rcp_iflag_f32_e32 v1, v1
	s_nop 0
	v_mul_f32_e32 v1, 0x4f7ffffe, v1
	v_cvt_u32_f32_e32 v1, v1
	s_nop 0
	v_readfirstlane_b32 s8, v1
	s_mul_i32 s3, s3, s8
	s_mul_hi_u32 s3, s8, s3
	s_add_i32 s8, s8, s3
	s_abs_i32 s3, s4
	s_mul_hi_u32 s10, s3, s8
	s_mul_i32 s11, s10, s2
	s_sub_i32 s3, s3, s11
	s_ashr_i32 s4, s4, 31
	s_xor_b32 s4, s4, s13
	s_add_i32 s11, s10, 1
	s_sub_i32 s12, s3, s2
	s_cmp_ge_u32 s3, s2
	s_cselect_b32 s10, s11, s10
	s_cselect_b32 s3, s12, s3
	s_add_i32 s11, s10, 1
	s_cmp_ge_u32 s3, s2
	s_cselect_b32 s3, s11, s10
	s_xor_b32 s3, s3, s4
	s_sub_i32 s3, s3, s4
	s_mul_i32 s12, s3, s14
	s_add_i32 s3, s12, s3
	s_min_i32 s11, s3, 0x200
	s_cmp_gt_i32 s11, s12
	s_cselect_b64 s[16:17], -1, 0
	s_abs_i32 s3, s6
	v_cvt_f32_u32_e32 v1, s3
	s_sub_i32 s4, 0, s3
	v_writelane_b32 v253, s16, 6
	v_rcp_iflag_f32_e32 v1, v1
	s_nop 0
	v_writelane_b32 v253, s17, 7
	v_writelane_b32 v253, s11, 8
	v_mul_f32_e32 v1, 0x4f7ffffe, v1
	v_cvt_u32_f32_e32 v1, v1
	s_nop 0
	v_readfirstlane_b32 s10, v1
	s_mul_i32 s4, s4, s10
	s_mul_hi_u32 s4, s10, s4
	s_add_i32 s10, s10, s4
	s_xor_b32 s4, s7, s6
	s_abs_i32 s6, s7
	s_mul_hi_u32 s7, s6, s10
	s_mul_i32 s10, s7, s3
	s_sub_i32 s6, s6, s10
	s_sub_i32 s10, s11, s12
	s_ashr_i32 s4, s4, 31
	v_writelane_b32 v253, s10, 9
	s_add_i32 s10, s7, 1
	s_sub_i32 s11, s6, s3
	s_cmp_ge_u32 s6, s3
	s_cselect_b32 s7, s10, s7
	s_cselect_b32 s6, s11, s6
	s_add_i32 s10, s7, 1
	s_cmp_ge_u32 s6, s3
	s_cselect_b32 s3, s10, s7
	s_xor_b32 s3, s3, s4
	s_sub_i32 s3, s3, s4
	s_mul_i32 s10, s3, s5
	s_add_i32 s3, s10, s3
	s_min_i32 s6, s3, 0x580
	s_cmp_gt_i32 s6, s10
	v_writelane_b32 v253, s6, 10
	s_cselect_b64 s[4:5], -1, 0
	v_writelane_b32 v253, s4, 11
	s_abs_i32 s3, s9
	s_sub_i32 s6, s6, s10
	v_writelane_b32 v253, s5, 12
	s_mul_hi_u32 s4, s3, s8
	s_mul_i32 s5, s4, s2
	s_sub_i32 s3, s3, s5
	s_ashr_i32 s5, s9, 31
	v_writelane_b32 v253, s13, 13
	s_xor_b32 s5, s5, s13
	v_writelane_b32 v253, s6, 14
	s_add_i32 s6, s4, 1
	s_sub_i32 s7, s3, s2
	s_cmp_ge_u32 s3, s2
	s_cselect_b32 s4, s6, s4
	s_cselect_b32 s3, s7, s3
	s_add_i32 s6, s4, 1
	s_cmp_ge_u32 s3, s2
	s_load_dword s3, s[0:1], 0x120
	v_lshrrev_b32_e32 v1, 20, v0
	v_lshrrev_b32_e32 v0, 10, v0
	v_or_b32_e32 v0, v0, v1
	s_movk_i32 s2, 0x3ff
	v_and_or_b32 v0, v0, s2, v163
	s_mul_i32 s2, s95, s94
	s_waitcnt lgkmcnt(0)
; #define LAS __attribute__((address_space(3)))
; __global__ void __launch_bounds__(512, 2) mega(Params p, int ph0, int ph1, int coop) {
;     extern __shared__ __attribute__((aligned(16))) unsigned char shm[];
;     LAS unsigned char* lds = (LAS unsigned char*)shm;
;     cg::grid_group grid = cg::this_grid();
;     volatile LAS unsigned* st = (volatile LAS unsigned*)(lds + LDS_BYTES);
;     if (threadIdx.x < 4) st[threadIdx.x] = 0u;
;     __syncthreads();
;     XcdBarrier xb = xcd_barrier_post((unsigned*)(p.ws + W_BAR), st);
;     for (int ph = ph0; ph < ph1; ++ph) {
	s_mul_i32 s2, s2, s3
	v_writelane_b32 v253, s2, 15
	s_cselect_b32 s2, s6, s4
	s_xor_b32 s2, s2, s5
	s_sub_i32 s2, s2, s5
	s_mul_i32 s3, s2, s14
	s_add_i32 s2, s3, s2
	s_min_i32 s2, s2, 0x800
	s_cmp_gt_i32 s2, s3
	s_cselect_b64 s[4:5], -1, 0
	v_writelane_b32 v253, s4, 16
	s_ashr_i32 s21, s28, 31
	v_mov_b32_e32 v1, 0
	v_writelane_b32 v253, s5, 17
	v_writelane_b32 v253, s2, 18
	s_sub_i32 s2, s2, s3
	v_writelane_b32 v253, s2, 19
	s_lshl_b32 s2, s94, 4
	v_writelane_b32 v253, s2, 20
	s_lshl_b32 s2, s14, 2
	v_writelane_b32 v253, s2, 21
	s_lshl_b32 s2, s94, 2
	v_writelane_b32 v253, s2, 22
	s_lshl_b32 s2, s14, 15
	v_writelane_b32 v253, s2, 23
	s_lshl_b32 s2, s94, 15
	v_writelane_b32 v253, s2, 24
	s_lshl_b64 s[4:5], s[20:21], 1
	v_writelane_b32 v253, s4, 25
	v_mov_b32_e32 v244, v1
	v_mov_b32_e32 v245, v1
	v_writelane_b32 v253, s5, 26
	s_lshl_b64 s[4:5], s[20:21], 2
	v_writelane_b32 v253, s4, 27
	s_mov_b32 s95, 0x800000
	s_mov_b64 s[28:29], 0x80
	v_writelane_b32 v253, s5, 28
	s_add_u32 s4, s88, 0x7225600
	s_addc_u32 s5, s89, 0
	v_writelane_b32 v253, s4, 29
	s_nop 1
	v_writelane_b32 v253, s5, 30
	s_add_u32 s4, s88, 0x7123600
	s_addc_u32 s5, s89, 0
	v_writelane_b32 v253, s4, 31
	s_lshl_b32 s2, s12, 1
	s_nop 0
	v_writelane_b32 v253, s5, 32
	v_writelane_b32 v253, s2, 33
	v_writelane_b32 v253, s12, 34
	s_lshl_b32 s2, s12, 4
	v_writelane_b32 v253, s2, 35
	s_lshl_b32 s2, s10, 4
	v_writelane_b32 v253, s2, 36
	s_lshl_b32 s2, s10, 2
	v_writelane_b32 v253, s2, 37
	v_writelane_b32 v253, s10, 38
	s_lshl_b32 s2, s10, 1
	v_writelane_b32 v253, s2, 39
	s_lshl_b32 s2, s14, 11
	v_writelane_b32 v253, s2, 40
	s_lshl_b32 s2, s94, 11
	v_writelane_b32 v253, s2, 41
	s_lshl_b32 s2, s14, 18
	v_writelane_b32 v253, s2, 42
	s_lshl_b32 s2, s94, 18
	v_writelane_b32 v253, s2, 43
	s_lshl_b32 s2, s14, 10
	v_writelane_b32 v253, s2, 44
	s_lshl_b32 s2, s94, 10
	v_writelane_b32 v253, s2, 45
	v_writelane_b32 v253, s14, 46
	s_lshl_b32 s2, s14, 7
	s_lshl_b64 s[4:5], s[20:21], 3
	v_writelane_b32 v253, s15, 47
	v_writelane_b32 v253, s2, 48
	s_lshl_b32 s2, s94, 7
	v_writelane_b32 v253, s2, 49
	v_writelane_b32 v253, s4, 50
	s_mul_i32 s2, s94, 24
	s_mov_b32 s21, 0x1ffff
	v_writelane_b32 v253, s5, 51
	s_add_u32 s4, s88, 0x7225800
	s_addc_u32 s5, s89, 0
	v_writelane_b32 v253, s4, 52
	s_nop 1
	v_writelane_b32 v253, s5, 53
	s_load_dwordx16 s[4:19], s[0:1], 0x0
	s_load_dwordx16 s[36:51], s[0:1], 0x40
	v_writelane_b32 v253, s2, 54
	s_lshl_b32 s2, s3, 1
	v_writelane_b32 v253, s2, 55
	v_writelane_b32 v253, s3, 56
	s_waitcnt lgkmcnt(0)
	v_writelane_b32 v254, s36, 0
	s_lshl_b32 s2, s3, 4
	v_writelane_b32 v253, s2, 57
	v_writelane_b32 v254, s37, 1
	v_writelane_b32 v254, s38, 2
	v_writelane_b32 v254, s39, 3
	v_writelane_b32 v254, s40, 4
	v_writelane_b32 v254, s41, 5
	v_writelane_b32 v254, s42, 6
	v_writelane_b32 v254, s43, 7
	v_writelane_b32 v254, s44, 8
	v_writelane_b32 v254, s45, 9
	v_writelane_b32 v254, s46, 10
	v_writelane_b32 v254, s47, 11
	v_writelane_b32 v254, s48, 12
	v_writelane_b32 v254, s49, 13
	v_writelane_b32 v254, s50, 14
	v_writelane_b32 v254, s51, 15
	s_load_dwordx16 s[36:51], s[0:1], 0x80
	s_mov_b32 s0, s94
	s_add_i32 s2, 0, 0x1a800
	v_writelane_b32 v253, s2, 58
	s_add_i32 s2, 0, 0x20004
	s_waitcnt lgkmcnt(0)
	v_writelane_b32 v254, s36, 16
	v_writelane_b32 v253, s2, 59
	s_mov_b32 s3, 0
	v_writelane_b32 v254, s37, 17
	v_writelane_b32 v254, s38, 18
	v_writelane_b32 v254, s39, 19
	v_writelane_b32 v254, s40, 20
	v_writelane_b32 v254, s41, 21
	v_writelane_b32 v254, s42, 22
	v_writelane_b32 v254, s43, 23
	v_writelane_b32 v254, s44, 24
	v_writelane_b32 v254, s45, 25
	v_writelane_b32 v254, s46, 26
	v_writelane_b32 v254, s47, 27
	v_writelane_b32 v254, s48, 28
	v_writelane_b32 v254, s49, 29
	v_writelane_b32 v254, s50, 30
	v_writelane_b32 v254, s51, 31
	v_writelane_b32 v254, s0, 32
	v_writelane_b32 v253, s2, 60
	s_nop 0
	v_writelane_b32 v254, s1, 33
	s_mov_b32 s0, s20
	v_writelane_b32 v254, s0, 34
	v_writelane_b32 v253, s3, 61
	v_cmp_eq_u32_e64 s[2:3], 0, v0
	v_writelane_b32 v254, s1, 35
	v_writelane_b32 v254, s54, 36
	v_writelane_b32 v253, s2, 62
	s_nop 0
	v_writelane_b32 v254, s55, 37
	v_writelane_b32 v254, s52, 38
	v_writelane_b32 v253, s3, 63
	s_nop 0
	v_writelane_b32 v254, s53, 39
	v_writelane_b32 v254, s60, 40
	s_nop 1
	v_writelane_b32 v254, s61, 41
	v_writelane_b32 v254, s58, 42
	s_nop 1
	v_writelane_b32 v254, s59, 43
	v_writelane_b32 v254, s84, 44
	s_nop 1
	v_writelane_b32 v254, s85, 45
	s_branch .LBB0_10

; #define LAS __attribute__((address_space(3)))
; __device__ void phase_m2(const Params& p, LAS unsigned char* lds, int l) {
;     for (int rr = 0; rr < 1 + ((REP_ITEM >> 4) & 1); ++rr) { if (IT_EN(4)) for (int it = blockIdx.x; it < 512; it += gridDim.x) ret_m2(p, lds, l, it >> 6, (it >> 1) & 31, it & 1); }
;     for (int rr = 0; rr < 1 + ((REP_ITEM >> 5) & 1); ++rr) { if (IT_EN(5)) for (int it = blockIdx.x; it < 512; it += gridDim.x) ssd_m2(p, lds, l, it >> 6, (it >> 1) & 31, it & 1); }
;     for (int rr = 0; rr < 1 + ((REP_ITEM >> 6) & 1); ++rr) { if (IT_EN(6)) for (int it = blockIdx.x; it < 256; it += gridDim.x) lru_item<2>(p, lds, l, it >> 5, it & 31); }
; }
.LBB0_296:
	s_and_b64 vcc, exec, s[0:1]
	s_cbranch_vccz .LBB0_359
	v_readlane_b32 s0, v250, 4
	s_nop 1
	s_bitcmp1_b32 s0, 6
	s_cbranch_scc0 .Lm2_normal
	s_mov_b32 s0, 1
	v_writelane_b32 v251, s0, 32
	s_branch .LBB0_358
.Lm2_normal:
	v_readlane_b32 s0, v250, 47
	v_readlane_b32 s1, v250, 48
	s_andn2_b64 vcc, exec, s[0:1]
	s_cbranch_vccnz .LBB0_358
.Lm2_ret_entry:
	v_readlane_b32 s40, v254, 16
	v_readlane_b32 s42, v254, 18
	v_readlane_b32 s0, v254, 54
	v_readlane_b32 s41, v254, 17
	v_readlane_b32 s43, v254, 19
	v_readlane_b32 s48, v254, 24
	v_readlane_b32 s49, v254, 25
	v_readlane_b32 s54, v254, 30
	v_readlane_b32 s55, v254, 31
	v_readlane_b32 s1, v254, 55
	s_add_u32 s40, s42, s0
	v_readlane_b32 s44, v254, 20
	v_readlane_b32 s45, v254, 21
	v_readlane_b32 s46, v254, 22
	v_readlane_b32 s47, v254, 23
	v_readlane_b32 s50, v254, 26
	v_readlane_b32 s51, v254, 27
	v_readlane_b32 s52, v254, 28
	s_addc_u32 s41, s43, s1
	v_readlane_b32 s0, v253, 46
	v_readlane_b32 s36, v250, 2
	v_readlane_b32 s48, v254, 38
	v_readlane_b32 s54, v254, 36
	v_readlane_b32 s58, v254, 42
	s_mov_b32 s26, s0
	v_readlane_b32 s37, v250, 3
	s_mov_b32 s30, 0x800000
	s_movk_i32 s42, 0x1000
	s_movk_i32 s43, 0x90
	s_movk_i32 s44, 0xc00
	s_mov_b32 s45, 0xf800
	s_mov_b32 s46, 0xc2fc0000
	s_mov_b32 s47, 0x3f2aaaab
	v_readlane_b32 s49, v254, 39
	s_mov_b32 s50, 0x33800000
	s_mov_b32 s51, 0x3f317218
	s_mov_b32 s52, 0x7245000
	v_readlane_b32 s55, v254, 37
	v_readlane_b32 s59, v254, 43
	s_mov_b64 s[56:57], 0x1000
	v_readlane_b32 s53, v254, 29
	v_readlane_b32 s1, v253, 47

; #define LAS __attribute__((address_space(3)))
; __device__ void phase_m2(const Params& p, LAS unsigned char* lds, int l) {
;     for (int rr = 0; rr < 1 + ((REP_ITEM >> 4) & 1); ++rr) { if (IT_EN(4)) for (int it = blockIdx.x; it < 512; it += gridDim.x) ret_m2(p, lds, l, it >> 6, (it >> 1) & 31, it & 1); }
;     for (int rr = 0; rr < 1 + ((REP_ITEM >> 5) & 1); ++rr) { if (IT_EN(5)) for (int it = blockIdx.x; it < 512; it += gridDim.x) ssd_m2(p, lds, l, it >> 6, (it >> 1) & 31, it & 1); }
;     for (int rr = 0; rr < 1 + ((REP_ITEM >> 6) & 1); ++rr) { if (IT_EN(6)) for (int it = blockIdx.x; it < 256; it += gridDim.x) lru_item<2>(p, lds, l, it >> 5, it & 31); }
; }
.LBB0_358:
	v_readlane_b32 s0, v250, 22
	v_readlane_b32 s1, v250, 23
	s_andn2_b64 vcc, exec, s[0:1]
	v_readlane_b32 s42, v253, 46
	s_mov_b32 s95, 0x800000
	s_movk_i32 s93, 0x1000
	v_readlane_b32 s43, v253, 47
	v_readlane_b32 s0, v251, 32
	s_nop 1
	s_cmp_eq_u32 s0, 2
	s_cbranch_scc0 .Lm2_358_cont
	s_mov_b32 s0, 0
	v_writelane_b32 v251, s0, 32
	s_branch .Lm2_359_cont
.Lm2_358_cont:
	s_cbranch_vccz .LBB0_366
.LBB0_359:
	v_readlane_b32 s0, v251, 32
	s_nop 1
	s_cmp_eq_u32 s0, 1
	s_cbranch_scc0 .Lm2_359_cont
	s_mov_b32 s0, 2
	v_writelane_b32 v251, s0, 32
	s_branch .Lm2_ret_entry

; __global__ void __launch_bounds__(512, 2) mega(Params p, int ph0, int ph1, int coop) {
;     ...
;     for (int ph = ph0; ph < ph1; ++ph) {
;         int reps = 1;
;     ...
;         { const int s = (ph == 0) ? 10 : (ph == NPHASE - 1 ? 11 : (ph - 1) % 7); if ((REP_MASK >> s) & 1) reps = 2; }
;     ...
;         for (int r = 0; r < reps; ++r) { run_phase(p, lds, ph); if (reps > 1) __syncthreads(); }
;         if (coop && ph + 1 < ph1) {
;             if (coop == 2) grid.sync();
;             xcd_barrier(xb);
;     ...
;             xcd_barrier(xb);
;     ...
;         }
;     }
.LBB0_666:
	v_readlane_b32 s0, v251, 29
	v_readlane_b32 s1, v251, 30
	s_mov_b64 s[40:41], s[0:1]
	s_add_i32 s40, s40, 1
	s_mov_b64 s[36:37], s[40:41]
	v_readlane_b32 s2, v251, 31
	v_readlane_b32 s3, v251, 32
	v_writelane_b32 v251, s36, 29
	s_cmp_ge_i32 s40, s41
	s_cselect_b64 s[0:1], -1, 0
	v_writelane_b32 v251, s37, 30
	v_writelane_b32 v251, s38, 31
	s_mov_b32 s39, 0
	v_writelane_b32 v251, s39, 32
	s_cmp_lt_i32 s40, s41
	v_readlane_b32 s22, v251, 27
	s_cselect_b64 s[2:3], -1, 0
	v_readlane_b32 s23, v251, 28
	s_and_b64 s[2:3], s[22:23], s[2:3]
	s_andn2_b64 vcc, exec, s[2:3]
	s_cbranch_vccz .LBB0_667
	s_getpc_b64 s[98:99]
